# pair handshake moved from tile start (behind the epilogue store drain) to the end of the K loop, where the only outstanding VMEM is one super-step old
# speedup vs baseline: 1.0215x; 1.0050x over previous
.Lg1_wd:
	s_barrier
	v_add_u32_e32 v130, s50, v212
	v_add_u32_e32 v131, s50, v213
	s_xor_b32 s16, s50, 0x8000
	s_add_u32 m0, s16, s52
	ds_read_b128 v[236:239], v192
	ds_read_b128 v[240:243], v192 offset:2048
	ds_read_b128 v[244:247], v192 offset:4096
	ds_read_b128 v[146:149], v192 offset:6144
	ds_read_b128 v[150:153], v193
	ds_read_b128 v[154:157], v193 offset:2048
	ds_read_b128 v[158:161], v193 offset:4096
	ds_read_b128 v[162:165], v193 offset:6144
	ds_read_b128 v[168:171], v130
	ds_read_b128 v[172:175], v130 offset:2048
	ds_read_b128 v[176:179], v130 offset:4096
	ds_read_b128 v[180:183], v130 offset:6144
	ds_read_b128 v[184:187], v130 offset:8192
	ds_read_b128 v[188:191], v130 offset:10240
	ds_read_b128 v[228:231], v130 offset:12288
	global_load_lds_dwordx4 v200, s[86:87]
	global_load_lds_dwordx4 v201, s[86:87] offset:1024
	global_load_lds_dwordx4 v202, s[86:87] offset:2048
	global_load_lds_dwordx4 v203, s[86:87] offset:3072
	s_add_u32 m0, m0, 0x1000
	s_nop 0
	global_load_lds_dwordx4 v204, s[86:87]
	global_load_lds_dwordx4 v205, s[86:87] offset:1024
	global_load_lds_dwordx4 v206, s[86:87] offset:2048
	global_load_lds_dwordx4 v207, s[86:87] offset:3072
	s_waitcnt lgkmcnt(7)
	s_barrier
; DEVI void lds_barrier() { asm volatile("s_waitcnt lgkmcnt(0)\n\ts_barrier" ::: "memory"); }
; #define SSTORE2(P, buf_) do { \
;     *(uint4*)(wA + (buf_) * 256 * GS2) = P##a0; *(uint4*)(wA + (buf_) * 256 * GS2 + 64 * GS2) = P##a1; \
;     *(uint4*)(wA + (buf_) * 256 * GS2 + 128 * GS2) = P##a2; *(uint4*)(wA + (buf_) * 256 * GS2 + 192 * GS2) = P##a3; \
;     *(uint4*)(wB + (buf_) * 128 * GS2) = P##b0; *(uint4*)(wB + (buf_) * 128 * GS2 + 64 * GS2) = P##b1; } while (0)
; DEVI void gemm_kloop2(const bf16_t* __restrict__ A, size_t lda, const bf16_t* __restrict__ Bt, size_t ldb,
;                       const bf16_t* __restrict__ nA, size_t nlda, const bf16_t* __restrict__ nBt, size_t nldb,
;                       bool first, bf16_t* smem, f32x4 (&acc)[8][4]) {
;     ...
; #pragma unroll 1
;   for (int kt = 0; kt < nk - 2; kt += 2) {
;     COMPUTE2(0, GLOAD2(x, gA, gB, lda, ldb, kt + 1));
;     SSTORE2(x, 1);
;     lds_barrier();
;     COMPUTE2(1, GLOAD2(x, gA, gB, lda, ldb, kt + 2));
;     SSTORE2(x, 0);
;     lds_barrier();
;   }
;   COMPUTE2(0, GLOAD2(x, gA, gB, lda, ldb, nk - 1));
;   SSTORE2(x, 1);
;   lds_barrier();
;   COMPUTE2(1, GLOAD2(x, hA, hB, nlda, nldb, 0));
;   SSTORE2(x, 0);
;   lds_barrier();
	s_mov_b32 m0, s53
	s_nop 0
	global_load_lds_dwordx4 v208, s[56:57]
	global_load_lds_dwordx4 v209, s[56:57] offset:1024
	global_load_lds_dwordx4 v210, s[56:57] offset:2048
	global_load_lds_dwordx4 v211, s[56:57] offset:3072
	ds_read_b128 v[232:235], v130 offset:14336
	s_waitcnt lgkmcnt(7)
	v_mfma_f32_16x16x32_bf16 v[114:117], v[236:239], v[168:171], v[114:117]
	v_mfma_f32_16x16x32_bf16 v[102:105], v[240:243], v[168:171], v[102:105]
	v_mfma_f32_16x16x32_bf16 v[94:97], v[244:247], v[168:171], v[94:97]
	v_mfma_f32_16x16x32_bf16 v[86:89], v[146:149], v[168:171], v[86:89]
	s_waitcnt lgkmcnt(6)
	v_mfma_f32_16x16x32_bf16 v[126:129], v[236:239], v[172:175], v[126:129]
	v_mfma_f32_16x16x32_bf16 v[122:125], v[240:243], v[172:175], v[122:125]
	ds_read_b128 v[168:171], v131
	v_mfma_f32_16x16x32_bf16 v[118:121], v[244:247], v[172:175], v[118:121]
	v_mfma_f32_16x16x32_bf16 v[110:113], v[146:149], v[172:175], v[110:113]
	s_waitcnt lgkmcnt(6)
	v_mfma_f32_16x16x32_bf16 v[106:109], v[236:239], v[176:179], v[106:109]
	v_mfma_f32_16x16x32_bf16 v[98:101], v[240:243], v[176:179], v[98:101]
	ds_read_b128 v[172:175], v131 offset:2048
	v_mfma_f32_16x16x32_bf16 v[90:93], v[244:247], v[176:179], v[90:93]
	v_mfma_f32_16x16x32_bf16 v[82:85], v[146:149], v[176:179], v[82:85]
	s_waitcnt lgkmcnt(6)
	v_mfma_f32_16x16x32_bf16 v[78:81], v[236:239], v[180:183], v[78:81]
	v_mfma_f32_16x16x32_bf16 v[74:77], v[240:243], v[180:183], v[74:77]
	ds_read_b128 v[176:179], v131 offset:4096
	v_mfma_f32_16x16x32_bf16 v[70:73], v[244:247], v[180:183], v[70:73]
	v_mfma_f32_16x16x32_bf16 v[66:69], v[146:149], v[180:183], v[66:69]
	s_waitcnt lgkmcnt(6)
	v_mfma_f32_16x16x32_bf16 v[62:65], v[236:239], v[184:187], v[62:65]
	v_mfma_f32_16x16x32_bf16 v[58:61], v[240:243], v[184:187], v[58:61]
	ds_read_b128 v[180:183], v131 offset:6144
	v_mfma_f32_16x16x32_bf16 v[54:57], v[244:247], v[184:187], v[54:57]
	v_mfma_f32_16x16x32_bf16 v[50:53], v[146:149], v[184:187], v[50:53]
	s_waitcnt lgkmcnt(6)
	v_mfma_f32_16x16x32_bf16 v[46:49], v[236:239], v[188:191], v[46:49]
	v_mfma_f32_16x16x32_bf16 v[42:45], v[240:243], v[188:191], v[42:45]
	ds_read_b128 v[184:187], v131 offset:8192
	v_mfma_f32_16x16x32_bf16 v[38:41], v[244:247], v[188:191], v[38:41]
	v_mfma_f32_16x16x32_bf16 v[34:37], v[146:149], v[188:191], v[34:37]
	s_waitcnt lgkmcnt(6)
	v_mfma_f32_16x16x32_bf16 v[30:33], v[236:239], v[228:231], v[30:33]
	v_mfma_f32_16x16x32_bf16 v[26:29], v[240:243], v[228:231], v[26:29]
	ds_read_b128 v[188:191], v131 offset:10240
	v_mfma_f32_16x16x32_bf16 v[22:25], v[244:247], v[228:231], v[22:25]
	v_mfma_f32_16x16x32_bf16 v[18:21], v[146:149], v[228:231], v[18:21]
	s_waitcnt lgkmcnt(6)
	v_mfma_f32_16x16x32_bf16 v[14:17], v[236:239], v[232:235], v[14:17]
	v_mfma_f32_16x16x32_bf16 v[10:13], v[240:243], v[232:235], v[10:13]
	ds_read_b128 v[228:231], v131 offset:12288
	v_mfma_f32_16x16x32_bf16 v[6:9], v[244:247], v[232:235], v[6:9]
	v_mfma_f32_16x16x32_bf16 v[2:5], v[146:149], v[232:235], v[2:5]
	s_waitcnt lgkmcnt(6)
	v_mfma_f32_16x16x32_bf16 v[114:117], v[150:153], v[168:171], v[114:117]
	v_mfma_f32_16x16x32_bf16 v[102:105], v[154:157], v[168:171], v[102:105]
	ds_read_b128 v[232:235], v131 offset:14336
	v_mfma_f32_16x16x32_bf16 v[94:97], v[158:161], v[168:171], v[94:97]
	v_mfma_f32_16x16x32_bf16 v[86:89], v[162:165], v[168:171], v[86:89]
	s_add_u32 s86, s86, 0x80
	s_waitcnt lgkmcnt(6)
	v_mfma_f32_16x16x32_bf16 v[126:129], v[150:153], v[172:175], v[126:129]
	v_mfma_f32_16x16x32_bf16 v[122:125], v[154:157], v[172:175], v[122:125]
	v_mfma_f32_16x16x32_bf16 v[118:121], v[158:161], v[172:175], v[118:121]
	v_mfma_f32_16x16x32_bf16 v[110:113], v[162:165], v[172:175], v[110:113]
	s_addc_u32 s87, s87, 0
	s_waitcnt lgkmcnt(5)
	v_mfma_f32_16x16x32_bf16 v[106:109], v[150:153], v[176:179], v[106:109]
	v_mfma_f32_16x16x32_bf16 v[98:101], v[154:157], v[176:179], v[98:101]
	v_mfma_f32_16x16x32_bf16 v[90:93], v[158:161], v[176:179], v[90:93]
	v_mfma_f32_16x16x32_bf16 v[82:85], v[162:165], v[176:179], v[82:85]
	s_add_u32 s56, s56, 0x80
	s_waitcnt lgkmcnt(4)
	v_mfma_f32_16x16x32_bf16 v[78:81], v[150:153], v[180:183], v[78:81]
	v_mfma_f32_16x16x32_bf16 v[74:77], v[154:157], v[180:183], v[74:77]
	v_mfma_f32_16x16x32_bf16 v[70:73], v[158:161], v[180:183], v[70:73]
	v_mfma_f32_16x16x32_bf16 v[66:69], v[162:165], v[180:183], v[66:69]
	s_addc_u32 s57, s57, 0
	s_waitcnt lgkmcnt(3)
	v_mfma_f32_16x16x32_bf16 v[62:65], v[150:153], v[184:187], v[62:65]
	v_mfma_f32_16x16x32_bf16 v[58:61], v[154:157], v[184:187], v[58:61]
	v_mfma_f32_16x16x32_bf16 v[54:57], v[158:161], v[184:187], v[54:57]
	v_mfma_f32_16x16x32_bf16 v[50:53], v[162:165], v[184:187], v[50:53]
	s_xor_b32 s50, s50, 0x8000
	s_waitcnt lgkmcnt(2)
	v_mfma_f32_16x16x32_bf16 v[46:49], v[150:153], v[188:191], v[46:49]
	v_mfma_f32_16x16x32_bf16 v[42:45], v[154:157], v[188:191], v[42:45]
	v_mfma_f32_16x16x32_bf16 v[38:41], v[158:161], v[188:191], v[38:41]
	v_mfma_f32_16x16x32_bf16 v[34:37], v[162:165], v[188:191], v[34:37]
	s_add_u32 s65, s65, 1
	s_waitcnt lgkmcnt(1)
	v_mfma_f32_16x16x32_bf16 v[30:33], v[150:153], v[228:231], v[30:33]
	v_mfma_f32_16x16x32_bf16 v[26:29], v[154:157], v[228:231], v[26:29]
	v_mfma_f32_16x16x32_bf16 v[22:25], v[158:161], v[228:231], v[22:25]
	v_mfma_f32_16x16x32_bf16 v[18:21], v[162:165], v[228:231], v[18:21]
	s_cmp_eq_u32 s65, 15
	s_waitcnt lgkmcnt(0)
	v_mfma_f32_16x16x32_bf16 v[14:17], v[150:153], v[232:235], v[14:17]
	v_mfma_f32_16x16x32_bf16 v[10:13], v[154:157], v[232:235], v[10:13]
	v_mfma_f32_16x16x32_bf16 v[6:9], v[158:161], v[232:235], v[6:9]
	v_mfma_f32_16x16x32_bf16 v[2:5], v[162:165], v[232:235], v[2:5]
	s_cselect_b64 s[86:87], s[58:59], s[86:87]
	s_cselect_b64 s[56:57], s[60:61], s[56:57]
	s_cmp_lt_u32 s65, 16
	s_cbranch_scc1 .Lg1_loop
	s_setprio 0
	s_add_u32 s82, s82, 1
	s_cmp_lg_u32 s52, 0
	s_cbranch_scc1 .Lg1_hsd
	s_cmp_lg_u32 s83, 64
	s_cbranch_scc1 .Lg1_hsd
	v_readlane_b32 s16, v251, 0
	s_lshl_b32 s17, s16, 2
	s_add_u32 s42, s0, 0xf83600
	s_addc_u32 s43, s1, 0
	s_add_u32 s44, s42, s17
	s_addc_u32 s45, s43, 0
	s_xor_b32 s17, s17, 0x400
	s_add_u32 s42, s42, s17
	s_addc_u32 s43, s43, 0
	s_or_b32 s18, s84, s82
	s_mov_b64 s[2:3], exec
	s_mov_b64 exec, 1
	v_mov_b32_e32 v130, s18
	v_mov_b32_e32 v131, 0
	global_store_dword v131, v130, s[44:45] sc0 sc1
	s_movk_i32 s19, 0x1000

; DEVI void phase_gemm_big(const Params& p, int mode, bf16_t* smem) {
;     ...
;     if (mode < 3) {
;       const int rm_cols = br == 0 ? 4352 : (br == 1 ? 2176 : 3072);
;       const int ld = br == 0 ? PC_LD : (br == 1 ? PA_LD : PB_LD);
;       if (n0 < rm_cols) {
.Lg1_hsd:
	s_nop 7
	s_nop 3
	v_add_u32_e32 v130, s36, v142
	s_cmpk_gt_i32 s34, 0x10ff
	v_ashrrev_i32_e32 v131, 31, v130
	s_mov_b64 s[2:3], -1
	s_cbranch_scc1 .LBB0_207
	s_andn2_b64 vcc, exec, s[2:3]
	s_cbranch_vccnz .LBB0_200
	s_branch .LBB0_208

; DEVI void phase_gemm_big(const Params& p, int mode, bf16_t* smem) {
;     ...
;     if (mode < 3) {
;       const int rm_cols = br == 0 ? 4352 : (br == 1 ? 2176 : 3072);
;       const int ld = br == 0 ? PC_LD : (br == 1 ? PA_LD : PB_LD);
;       if (n0 < rm_cols) {
.Lg2_hsd:
	s_nop 7
	s_nop 3
	v_add_u32_e32 v130, s36, v142
	s_cmpk_gt_i32 s34, 0x87f
	v_ashrrev_i32_e32 v131, 31, v130
	s_mov_b64 s[2:3], -1
	s_cbranch_scc1 .LBB0_633
	s_andn2_b64 vcc, exec, s[2:3]
	s_cbranch_vccnz .LBB0_626
	s_branch .LBB0_634

; DEVI void phase_gemm_big(const Params& p, int mode, bf16_t* smem) {
;     ...
;     if (mode < 3) {
;       const int rm_cols = br == 0 ? 4352 : (br == 1 ? 2176 : 3072);
;       const int ld = br == 0 ? PC_LD : (br == 1 ? PA_LD : PB_LD);
;       if (n0 < rm_cols) {
.Lg3_hsd:
	s_nop 7
	s_nop 3
	v_add_u32_e32 v130, s36, v142
	s_cmpk_gt_i32 s34, 0xbff
	v_ashrrev_i32_e32 v131, 31, v130
	s_mov_b64 s[2:3], -1
	s_cbranch_scc1 .LBB0_1119
	s_andn2_b64 vcc, exec, s[2:3]
	s_cbranch_vccnz .LBB0_1112
	s_branch .LBB0_1120
